# in-projection split: 3 rounds of tiles needed first, grid barrier, then mem_q/mem_gate/mem-KV tiles + conversions overlap the mixer phase start; mem attention waits on a completion counter
# speedup vs baseline: 1.0278x; 1.0027x over previous
; #define LAS __attribute__((address_space(3)))
; __global__ void __launch_bounds__(512, 2) hymba_fwd(Params p) {
;     extern __shared__ __attribute__((aligned(16))) unsigned char lds_raw[];
;     LAS unsigned char* lds = (LAS unsigned char*)lds_raw;
;     const int tid = threadIdx.x;
;     const int G = gridDim.x; const int bx = blockIdx.x; const int vcu = (G % 8 == 0) ? (bx % 8) * (G / 8) + bx / 8 : bx;
;     volatile LAS unsigned* ctlw = (volatile LAS unsigned*)(lds + LDS_CTLW);
;     if (tid < 128) ctlw[tid] = 0u;
;     __syncthreads();
;     unsigned* ctl = (unsigned*)(p.ws + WS_CTL);
;     const int lo = p.ph_lo, hi = p.ph_hi;
;     XcdBarrier bar; bar.bar = ctl + CW_BAR; bar.x = 0; bar.st = nullptr;
;     if (hi - lo > 1) bar = xcd_barrier_post(ctl + CW_BAR, ctlw + 8);
_Z9hymba_fwd6Params:
	s_mov_b32 s98, 0
	s_mov_b32 s95, s2
	s_load_dword s2, s[0:1], 0xe8
	s_load_dwordx2 s[6:7], s[0:1], 0xe0
	s_add_u32 s4, s0, 0xe8
	s_addc_u32 s5, s1, 0
	v_writelane_b32 v254, s4, 0
	s_nop 1
	v_writelane_b32 v254, s5, 1
	s_waitcnt lgkmcnt(0)
	v_writelane_b32 v254, s2, 2
	s_and_b32 s2, s2, 7
	s_cmp_lg_u32 s2, 0
	s_mov_b32 s4, s95
	s_cbranch_scc1 .LBB0_2
	s_load_dword s2, s[0:1], 0xe8
	s_ashr_i32 s3, s95, 31
	s_lshr_b32 s3, s3, 29
	s_add_i32 s3, s95, s3
	s_and_b32 s4, s3, -8
	s_waitcnt lgkmcnt(0)
	s_ashr_i32 s2, s2, 3
	s_sub_i32 s4, s95, s4
	s_mul_i32 s2, s2, s4
	s_ashr_i32 s3, s3, 3
	s_add_i32 s4, s2, s3

; #define LAS __attribute__((address_space(3)))
;     __device__ bool next(int i, Unit& u) const {
;         const long L = (long)i * G + c;
;         if (L >= nwg + n1M * n1N) return false;
;         if (L >= nwg) { const int r = (int)L - nwg; u.pm = r / n1N; u.pn = r % n1N; u.sel = 1; return true; }
;         int wgid = (int)L; { const int q = nwg / NXCD, r = nwg % NXCD, xcd = wgid % NXCD, off = wgid / NXCD; wgid = (xcd < r ? xcd * (q + 1) : r * (q + 1) + (xcd - r) * q) + off; }
;         const int nig = wgm * nN, gid = wgid / nig, fm = gid * wgm, gsz = (nM - fm) < wgm ? (nM - fm) : wgm;
;         u.pm = fm + ((wgid % nig) % gsz); u.pn = (wgid % nig) / gsz; u.sel = 0; return true;
;     }
; __global__ void __launch_bounds__(512, 2) hymba_fwd(Params p) {
;     ...
;         pg8::Gemm g{(const bf16_t*)(p.ws + WS_H), (const bf16_t*)(p.ws + WS_WIN), (const bf16_t*)(p.ws + WS_HM), (const bf16_t*)(p.ws + WS_WM), DM};
;         pg8::Order S; S.init(MROWS / 256, NPAD / 256, MMEM / 256, 1024 / 256, G, bx, 4);
;         Epi1 E{(bf16_t*)(p.ws + WS_PROJ), (float*)(p.ws + WS_DT), p.out, p.in[I_DTBIAS], p.in[I_QNORM], p.in[I_KNORM], p.in[I_MQNORM], p.in[I_MKNORM], (bf16_t*)(p.ws + WS_MKN), (bf16_t*)(p.ws + WS_MVB), (LAS float*)(lds + RING_BYTES)};
;         pg8::gemm_phase<Epi1>(lds, g, S, E);
.LBB0_238:
	s_cmp_gt_i32 s6, 1
	s_cselect_b64 s[0:1], -1, 0
	s_cmp_lt_i32 s7, 2
	s_cselect_b64 s[2:3], -1, 0
	s_or_b64 s[0:1], s[0:1], s[2:3]
	s_and_b64 vcc, exec, s[0:1]
	s_cbranch_vccnz .LBB0_626
	v_readfirstlane_b32 s10, v0
	s_mov_b32 s4, s95
	s_cmp_lg_u32 s98, 0
	s_cbranch_scc1 .Lord1_B
	s_cmpk_lt_u32 s4, 0x2f7
	s_cselect_b64 s[0:1], -1, 0
	s_and_b32 s5, s4, 7
	s_lshr_b32 s6, s4, 3
	s_mul_i32 s5, s5, 0x5f
	s_add_i32 s5, s5, s6
	s_mul_hi_u32 s6, s5, 0x2c8590c
	s_mul_i32 s7, s6, 0x5c
	s_sub_i32 s7, s5, s7
	s_lshl_b32 s34, s6, 2
	s_and_b32 s5, s7, 3
	s_add_i32 s34, s34, s5
	s_lshr_b32 s62, s7, 2
	s_cmp_eq_u32 s6, 8
	s_cselect_b32 s34, 32, s34
	s_cselect_b32 s62, s7, s62
	s_cmp_eq_u32 s62, 22
	s_cselect_b32 s62, 26, s62
	s_mov_b32 s70, 0
	s_branch .Lord1_done
.Lord1_B:
	s_cmpk_lt_u32 s4, 0x94
	s_cselect_b64 s[0:1], -1, 0
	s_cmpk_lt_u32 s4, 0x84
	s_cbranch_scc1 .Lord1_Bg
	s_sub_i32 s5, s4, 0x84
	s_lshr_b32 s34, s5, 2
	s_and_b32 s62, s5, 3
	s_mov_b32 s70, 1
	s_branch .Lord1_done
.Lord1_Bg:
	s_and_b32 s5, s4, 7
	s_lshr_b32 s6, s4, 3
	s_mul_i32 s7, s5, 17
	s_lshl_b32 s3, s5, 4
	s_add_i32 s3, s3, 4
	s_cmp_lt_u32 s5, 4
	s_cselect_b32 s5, s7, s3
	s_add_i32 s5, s5, s6
	s_lshr_b32 s34, s5, 2
	s_and_b32 s62, s5, 3
	s_add_i32 s62, s62, 22
	s_mov_b32 s70, 0
.Lord1_done:
	s_cmp_eq_u32 s70, 0
	s_cselect_b64 s[2:3], -1, 0

;     __device__ bool next(int i, Unit& u) const {
;         const long L = (long)i * G + c;
;         if (L >= nwg + n1M * n1N) return false;
;         if (L >= nwg) { const int r = (int)L - nwg; u.pm = r / n1N; u.pn = r % n1N; u.sel = 1; return true; }
;         int wgid = (int)L; { const int q = nwg / NXCD, r = nwg % NXCD, xcd = wgid % NXCD, off = wgid / NXCD; wgid = (xcd < r ? xcd * (q + 1) : r * (q + 1) + (xcd - r) * q) + off; }
;         const int nig = wgm * nN, gid = wgid / nig, fm = gid * wgm, gsz = (nM - fm) < wgm ? (nM - fm) : wgm;
;         u.pm = fm + ((wgid % nig) % gsz); u.pn = (wgid % nig) / gsz; u.sel = 0; return true;
;     }
; template <class Epi>
; __device__ __forceinline__ void gemm_phase(LAS unsigned char* lds, const Gemm g, const Order& S, const Epi& E) {
;     ...
;     for (;;) {
;         const bool has_next = S.next(ui + 1, nxt);
;         const char* nA = has_next ? (const char*)(nxt.sel ? g.A1 : g.A0) + (size_t)nxt.pm * tstep : cA; const char* nB = has_next ? (const char*)(nxt.sel ? g.B1 : g.B0) + (size_t)nxt.pn * tstep : cB;
;         for (int t = 0; t < nt; t += 2) {
;             const bool last = (t == nt - 2);
;             const char* a1 = cA + (size_t)(t + 1) * kstep;
;             const char* a2 = last ? nA : cA + (size_t)(t + 2) * kstep; const char* b2 = last ? nB : cB + (size_t)(t + 2) * kstep;
;             const char* a3 = a2 + kstep; const char* b3 = b2 + kstep;
;             if constexpr (Epi::MID > 0) { if (t == Epi::MID) E.mid(acc, cur, wr, fr); }
;             PG8_LDB(B0, 0, 0); PG8_LDB(B1, 0, 1); PG8_SCHED; PG8_LDA(At, 0, 0); PG8_STAGE(PG8_SA(1, 1), a1 + hstep);
;             PG8_WAIT_V(8); PG8_WAIT_L(0); PG8_BAR; PG8_MMA(0, 0, At, B0); PG8_MMA(0, 1, At, B1); PG8_BAR; PG8_SCHED;
;             PG8_LDA(At, 0, 1); PG8_STAGE(PG8_SB(0, 0), b2); PG8_STAGE(PG8_SB(0, 1), b2 + hstep); PG8_STAGE(PG8_SA(0, 0), a2);
;             PG8_WAIT_V(8); PG8_WAIT_L(0); PG8_BAR; PG8_MMA(1, 0, At, B0); PG8_MMA(1, 1, At, B1); PG8_BAR; PG8_SCHED;
;             PG8_LDB(B0, 1, 0); PG8_LDB(B1, 1, 1); PG8_SCHED; PG8_LDA(At, 1, 0); PG8_STAGE(PG8_SA(0, 1), a2 + hstep);
;             PG8_WAIT_V(8); PG8_WAIT_L(0); PG8_BAR; PG8_MMA(0, 0, At, B0); PG8_MMA(0, 1, At, B1); PG8_BAR; PG8_SCHED;
;             PG8_LDA(At, 1, 1); PG8_STAGE(PG8_SB(1, 0), b3); PG8_STAGE(PG8_SB(1, 1), b3 + hstep); PG8_STAGE(PG8_SA(1, 0), a3);
.LBB0_255:
	s_add_i32 s20, s20, 1
	s_lshl_b32 s28, s20, 8
	s_add_i32 s28, s28, s95
	s_cmp_lg_u32 s98, 0
	s_cbranch_scc1 .Lord2_B
	s_cmpk_lt_u32 s28, 0x2f7
	s_cselect_b64 s[4:5], -1, 0
	s_and_b32 s23, s28, 7
	s_lshr_b32 s24, s28, 3
	s_mul_i32 s23, s23, 0x5f
	s_add_i32 s23, s23, s24
	s_mul_hi_u32 s24, s23, 0x2c8590c
	s_mul_i32 s25, s24, 0x5c
	s_sub_i32 s25, s23, s25
	s_lshl_b32 s26, s24, 2
	s_and_b32 s23, s25, 3
	s_add_i32 s26, s26, s23
	s_lshr_b32 s22, s25, 2
	s_cmp_eq_u32 s24, 8
	s_cselect_b32 s26, 32, s26
	s_cselect_b32 s22, s25, s22
	s_cmp_eq_u32 s22, 22
	s_cselect_b32 s22, 26, s22
	s_mov_b32 s16, 0
	s_branch .Lord2_done
.Lord2_B:
	s_cmpk_lt_u32 s28, 0x94
	s_cselect_b64 s[4:5], -1, 0
	s_cmpk_lt_u32 s28, 0x84
	s_cbranch_scc1 .Lord2_Bg
	s_sub_i32 s23, s28, 0x84
	s_lshr_b32 s26, s23, 2
	s_and_b32 s22, s23, 3
	s_mov_b32 s16, 1
	s_branch .Lord2_done
.Lord2_Bg:
	s_and_b32 s23, s28, 7
	s_lshr_b32 s24, s28, 3
	s_mul_i32 s25, s23, 17
	s_lshl_b32 s27, s23, 4
	s_add_i32 s27, s27, 4
	s_cmp_lt_u32 s23, 4
	s_cselect_b32 s23, s25, s27
	s_add_i32 s23, s23, s24
	s_lshr_b32 s26, s23, 2
	s_and_b32 s22, s23, 3
	s_add_i32 s22, s22, 22
	s_mov_b32 s16, 0
.Lord2_done:
.LBB0_264:
	s_ashr_i32 s27, s26, 31
	s_lshl_b64 s[28:29], s[26:27], 20
	s_cmp_eq_u32 s16, 0
	v_readlane_b32 s23, v254, 13
	v_readlane_b32 s24, v254, 14
	s_cselect_b32 s23, s23, s24
	v_readlane_b32 s24, v254, 15
	v_readlane_b32 s25, v254, 16
	s_cselect_b32 s24, s24, s25
	v_readlane_b32 s25, v254, 11
	v_readlane_b32 s27, v254, 12
	s_cselect_b32 s25, s25, s27
	v_readlane_b32 s27, v254, 10
	s_cselect_b32 s54, s27, s17
	s_add_u32 s28, s24, s28
	s_addc_u32 s29, s23, s29
	s_and_b64 s[30:31], s[4:5], exec
	s_cselect_b32 s27, s29, s7
	s_cselect_b32 s35, s28, s6
	s_ashr_i32 s23, s22, 31
	s_lshl_b64 s[30:31], s[22:23], 20
	s_add_u32 s30, s25, s30
	s_addc_u32 s31, s54, s31
	s_and_b64 s[54:55], s[4:5], exec
	s_cselect_b32 s23, s31, s9
	s_cselect_b32 s71, s30, s8
	s_add_u32 s6, s6, 0x80080
	s_addc_u32 s7, s7, 0
	s_add_u32 s72, s8, 0x100
	v_mov_b32_e32 v34, 0
	s_addc_u32 s73, s9, 0
	s_mov_b32 s94, -2
	v_mov_b32_e32 v35, v34
	v_mov_b32_e32 v36, v34
	v_mov_b32_e32 v37, v34
	v_mov_b32_e32 v38, v34
	v_mov_b32_e32 v39, v34
	v_mov_b32_e32 v40, v34
	v_mov_b32_e32 v41, v34
	v_mov_b32_e32 v46, v34
	v_mov_b32_e32 v47, v34
	v_mov_b32_e32 v48, v34
	v_mov_b32_e32 v49, v34
	v_mov_b32_e32 v50, v34
	v_mov_b32_e32 v51, v34
	v_mov_b32_e32 v52, v34
	v_mov_b32_e32 v53, v34
	v_mov_b32_e32 v58, v34
	v_mov_b32_e32 v59, v34
	v_mov_b32_e32 v60, v34
	v_mov_b32_e32 v61, v34
	v_mov_b32_e32 v62, v34
	v_mov_b32_e32 v63, v34
	v_mov_b32_e32 v64, v34
	v_mov_b32_e32 v65, v34
	v_mov_b32_e32 v70, v34
	v_mov_b32_e32 v71, v34
	v_mov_b32_e32 v72, v34
	v_mov_b32_e32 v73, v34
	v_mov_b32_e32 v74, v34
	v_mov_b32_e32 v75, v34
	v_mov_b32_e32 v76, v34
	v_mov_b32_e32 v77, v34
	v_mov_b32_e32 v42, v34
	v_mov_b32_e32 v43, v34
	v_mov_b32_e32 v44, v34
	v_mov_b32_e32 v45, v34
	v_mov_b32_e32 v2, v34
	v_mov_b32_e32 v3, v34
	v_mov_b32_e32 v4, v34
	v_mov_b32_e32 v5, v34
	v_mov_b32_e32 v54, v34
	v_mov_b32_e32 v55, v34
	v_mov_b32_e32 v56, v34
	v_mov_b32_e32 v57, v34
	v_mov_b32_e32 v6, v34
	v_mov_b32_e32 v7, v34
	v_mov_b32_e32 v8, v34
	v_mov_b32_e32 v9, v34
	v_mov_b32_e32 v66, v34
	v_mov_b32_e32 v67, v34
	v_mov_b32_e32 v68, v34
	v_mov_b32_e32 v69, v34
	v_mov_b32_e32 v10, v34
	v_mov_b32_e32 v11, v34
	v_mov_b32_e32 v12, v34
	v_mov_b32_e32 v13, v34
	v_mov_b32_e32 v78, v34
	v_mov_b32_e32 v79, v34
	v_mov_b32_e32 v80, v34
	v_mov_b32_e32 v81, v34
	v_mov_b32_e32 v14, v34
	v_mov_b32_e32 v15, v34
	v_mov_b32_e32 v16, v34
	v_mov_b32_e32 v17, v34
	v_mov_b32_e32 v82, v34
	v_mov_b32_e32 v83, v34
	v_mov_b32_e32 v84, v34
	v_mov_b32_e32 v85, v34
	v_mov_b32_e32 v86, v34
	v_mov_b32_e32 v87, v34
	v_mov_b32_e32 v88, v34
	v_mov_b32_e32 v89, v34
	v_mov_b32_e32 v94, v34
	v_mov_b32_e32 v95, v34
	v_mov_b32_e32 v96, v34
	v_mov_b32_e32 v97, v34
	v_mov_b32_e32 v98, v34
	v_mov_b32_e32 v99, v34
	v_mov_b32_e32 v100, v34
	v_mov_b32_e32 v101, v34
	v_mov_b32_e32 v106, v34
	v_mov_b32_e32 v107, v34
	v_mov_b32_e32 v108, v34
	v_mov_b32_e32 v109, v34
	v_mov_b32_e32 v110, v34
	v_mov_b32_e32 v111, v34
	v_mov_b32_e32 v112, v34
	v_mov_b32_e32 v113, v34
	v_mov_b32_e32 v118, v34
	v_mov_b32_e32 v119, v34
	v_mov_b32_e32 v120, v34
	v_mov_b32_e32 v121, v34
	v_mov_b32_e32 v122, v34
	v_mov_b32_e32 v123, v34
	v_mov_b32_e32 v124, v34
	v_mov_b32_e32 v125, v34
	v_mov_b32_e32 v90, v34
	v_mov_b32_e32 v91, v34
	v_mov_b32_e32 v92, v34
	v_mov_b32_e32 v93, v34
	v_mov_b32_e32 v18, v34
	v_mov_b32_e32 v19, v34
	v_mov_b32_e32 v20, v34
	v_mov_b32_e32 v21, v34
	v_mov_b32_e32 v102, v34
	v_mov_b32_e32 v103, v34
	v_mov_b32_e32 v104, v34
	v_mov_b32_e32 v105, v34
	v_mov_b32_e32 v22, v34
	v_mov_b32_e32 v23, v34
	v_mov_b32_e32 v24, v34
	v_mov_b32_e32 v25, v34
	v_mov_b32_e32 v114, v34
	v_mov_b32_e32 v115, v34
	v_mov_b32_e32 v116, v34
	v_mov_b32_e32 v117, v34
	v_mov_b32_e32 v26, v34
	v_mov_b32_e32 v27, v34
	v_mov_b32_e32 v28, v34
	v_mov_b32_e32 v29, v34
	v_mov_b32_e32 v126, v34
	v_mov_b32_e32 v127, v34
	v_mov_b32_e32 v128, v34
	v_mov_b32_e32 v129, v34
	v_mov_b32_e32 v30, v34
	v_mov_b32_e32 v31, v34
	v_mov_b32_e32 v32, v34
	v_mov_b32_e32 v33, v34

; #define LAS __attribute__((address_space(3)))
; __global__ void __launch_bounds__(512, 2) hymba_fwd(Params p) {
;     ...
;         {
;             const int nfull = (MROWS / 256) * (NPAD / 256) + (MMEM / 256) * (1024 / 256) - ((MROWS / 256) * (NPAD / 256) + (MMEM / 256) * (1024 / 256)) / G * G;
;             const int first_idle = (nfull == 0) ? 0 : nfull, nidle = G - first_idle;
;             if (bx >= first_idle) {
;                 const int lane = tid & 63, wave = __builtin_amdgcn_readfirstlane(tid >> 6);
;                 tr_pipeline(p, (LAS float*)(lds + wave * 16896), lane, (bx - first_idle) * 8 + wave, nidle * 8, NITEMS_P0, NITEMS_ALL);
;                 cache_mem_convert(p, (bx - first_idle) * 512 + tid, nidle * 512);
;             }
.LBB0_458:
	s_cmp_eq_u32 s98, 0
	s_cbranch_scc1 .LBB0_576
	v_readlane_b32 s0, v254, 2
	s_abs_i32 s0, s0
	s_sub_i32 s1, 0, s0
	s_waitcnt vmcnt(0)
	v_cvt_f32_u32_e32 v2, s0
	v_rcp_iflag_f32_e32 v2, v2
	s_nop 0
	v_mul_f32_e32 v2, 0x4f7ffffe, v2
	v_cvt_u32_f32_e32 v2, v2
	s_nop 0
	v_readfirstlane_b32 s2, v2
	s_mul_i32 s1, s1, s2
	s_mul_hi_u32 s1, s2, s1
	s_add_i32 s2, s2, s1
	s_mul_hi_u32 s1, s2, 0x38b
	s_mul_i32 s1, s1, s0
	s_sub_i32 s1, 0x38b, s1
	s_sub_i32 s2, s1, s0
	s_cmp_ge_u32 s1, s0
	s_cselect_b32 s1, s2, s1
	s_sub_i32 s2, s1, s0
	s_cmp_ge_u32 s1, s0
	s_cselect_b32 s2, s2, s1
	s_movk_i32 s2, 0x94
	s_cmp_lt_i32 s95, s2
	s_cbranch_scc1 .LBB0_576
	v_readfirstlane_b32 s0, v0
	s_sub_i32 s20, s95, s2
	s_lshr_b32 s4, s0, 6
	s_lshl_b32 s0, s20, 3
	v_and_b32_e32 v4, 63, v0
	s_add_i32 s3, s4, s0
	s_cmpk_lt_u32 s3, 0x400
	v_lshrrev_b32_e32 v2, 5, v4
	v_lshrrev_b32_e32 v3, 1, v0
	s_cbranch_scc1 .LBB0_461
	v_and_b32_e32 v140, 0x7c, v166
	v_lshrrev_b32_e32 v141, 5, v4
	v_and_b32_e32 v134, 24, v3
	v_mov_b32_e32 v135, 0
	s_mov_b64 s[0:1], 0
	v_mov_b64_e32 v[136:137], 0
	s_andn2_b64 vcc, exec, s[0:1]
	v_mov_b64_e32 v[4:5], 0
	s_cbranch_vccnz .LBB0_463
	s_branch .LBB0_462

; #define LAS __attribute__((address_space(3)))
; #define STAMP() do { if (PROBE_SEG >= 0 && bx == 0 && tid == 0) { tst[nst] = __builtin_amdgcn_s_memrealtime(); } ++nst; } while (0)
; #define BOTH(k) (IN(k) && IN((k) + 1))
; __global__ void __launch_bounds__(512, 2) hymba_fwd(Params p) {
;     ...
;         pg8::gemm_phase<Epi1>(lds, g, S, E);
;         {
;             const int nfull = (MROWS / 256) * (NPAD / 256) + (MMEM / 256) * (1024 / 256) - ((MROWS / 256) * (NPAD / 256) + (MMEM / 256) * (1024 / 256)) / G * G;
;             const int first_idle = (nfull == 0) ? 0 : nfull, nidle = G - first_idle;
;             if (bx >= first_idle) {
;                 const int lane = tid & 63, wave = __builtin_amdgcn_readfirstlane(tid >> 6);
;                 tr_pipeline(p, (LAS float*)(lds + wave * 16896), lane, (bx - first_idle) * 8 + wave, nidle * 8, NITEMS_P0, NITEMS_ALL);
;                 cache_mem_convert(p, (bx - first_idle) * 512 + tid, nidle * 512);
;             }
;         }
;         if (BOTH(1)) GBAR(); STAMP();
;     }
;     if (IN(3)) { phase3<31>(p, lds, ctlw, 0); if (BOTH(3)) GBAR(); STAMP(); }
.LBB0_576:
	s_cmp_eq_u32 s98, 1
	s_cbranch_scc0 .Lp1_bar
	s_mov_b32 s98, 2
	s_waitcnt vmcnt(0) lgkmcnt(0)
	s_barrier
	v_cmp_eq_u32_e32 vcc, 0, v0
	s_and_saveexec_b64 s[0:1], vcc
	s_cbranch_execz .Lp1_pub_done
	buffer_wbl2 sc1
	s_waitcnt vmcnt(0)
	v_mov_b32_e32 v1, 0x800
	v_mov_b32_e32 v2, 1
	global_atomic_add v1, v2, s[90:91]
	s_waitcnt vmcnt(0)
.Lp1_pub_done:
	s_or_b64 exec, exec, s[0:1]
	v_readlane_b32 s6, v254, 3
	v_readlane_b32 s7, v254, 4
	s_branch .LBB0_626

; #define LAS __attribute__((address_space(3)))
; #define STAMP() do { if (PROBE_SEG >= 0 && bx == 0 && tid == 0) { tst[nst] = __builtin_amdgcn_s_memrealtime(); } ++nst; } while (0)
; #define BOTH(k) (IN(k) && IN((k) + 1))
; __global__ void __launch_bounds__(512, 2) hymba_fwd(Params p) {
;     ...
;     if (IN(1)) {
;         pg8::Gemm g{(const bf16_t*)(p.ws + WS_H), (const bf16_t*)(p.ws + WS_WIN), (const bf16_t*)(p.ws + WS_HM), (const bf16_t*)(p.ws + WS_WM), DM};
;         pg8::Order S; S.init(MROWS / 256, NPAD / 256, MMEM / 256, 1024 / 256, G, bx, 4);
;         Epi1 E{(bf16_t*)(p.ws + WS_PROJ), (float*)(p.ws + WS_DT), p.out, p.in[I_DTBIAS], p.in[I_QNORM], p.in[I_KNORM], p.in[I_MQNORM], p.in[I_MKNORM], (bf16_t*)(p.ws + WS_MKN), (bf16_t*)(p.ws + WS_MVB), (LAS float*)(lds + RING_BYTES)};
;         pg8::gemm_phase<Epi1>(lds, g, S, E);
;         {
;             const int nfull = (MROWS / 256) * (NPAD / 256) + (MMEM / 256) * (1024 / 256) - ((MROWS / 256) * (NPAD / 256) + (MMEM / 256) * (1024 / 256)) / G * G;
;             const int first_idle = (nfull == 0) ? 0 : nfull, nidle = G - first_idle;
;             if (bx >= first_idle) {
;                 const int lane = tid & 63, wave = __builtin_amdgcn_readfirstlane(tid >> 6);
;                 tr_pipeline(p, (LAS float*)(lds + wave * 16896), lane, (bx - first_idle) * 8 + wave, nidle * 8, NITEMS_P0, NITEMS_ALL);
;                 cache_mem_convert(p, (bx - first_idle) * 512 + tid, nidle * 512);
;             }
;         }
;         if (BOTH(1)) GBAR(); STAMP();
;     }
;     if (IN(3)) { phase3<31>(p, lds, ctlw, 0); if (BOTH(3)) GBAR(); STAMP(); }
.LBB0_626:
	s_cmp_lg_u32 s98, 0
	s_cbranch_scc1 .Lp3_enter
	s_mov_b32 s98, 1
	v_readlane_b32 s2, v254, 0
	v_readlane_b32 s3, v254, 1
	s_sub_u32 s2, s2, 0xe8
	s_subb_u32 s3, s3, 0
	s_load_dwordx4 s[48:51], s[2:3], 0x30
	s_load_dwordx2 s[54:55], s[2:3], 0x88
	v_readlane_b32 s95, v254, 9
	v_readlane_b32 s6, v254, 3
	v_readlane_b32 s7, v254, 4
	s_waitcnt lgkmcnt(0)
	s_branch .LBB0_238

; #define GROUP_LOOP(qi, total, ...) for (int gi_ = 0;; ++gi_) { if (threadIdx.x == 0) ctlw[22 + (gi_ & 1)] = __hip_atomic_fetch_add(qbase + 64 * (qi), 1u, __ATOMIC_RELAXED, __HIP_MEMORY_SCOPE_AGENT); \
;         group_bar(gb, lane); const int u = (int)ctlw[22 + (gi_ & 1)]; if (u >= (total)) break; __VA_ARGS__ }
; template <int MASK> __device__ __forceinline__ void phase3(const Params& p, LAS unsigned char* lds, volatile LAS unsigned* ctlw, int qset) {
;     ...
;             GROUP_LOOP(3, U_MEMP + U_MEMS, {
;                 if (u < U_MEMP) { const int hm = u & 3, qb = (u >> 2) & 15, b = u >> 6; const size_t r0 = (size_t)(b * SEQ + qb * 128);
;                     attn_unit<1>(lds, gb, PROJ + r0 * NPAD + PC_MQ + hm * 128, NPAD, (const bf16_t*)(p.ws + WS_MKN) + (size_t)(b * MEMT) * 512 + hm * 128, (const bf16_t*)(p.ws + WS_MVB) + (size_t)(b * MEMT) * 512 + hm * 128, 512,
;                                  4, 0, 128, 0.f, PROJ + r0 * NPAD + PC_GM + hm * 128, NPAD, MIX + r0 * 2048 + 1536 + hm * 128, 2048); }
;                 else { const int v = u - U_MEMP, hm = v & 3, sq = v >> 2; const size_t r0 = (size_t)(MP + sq * DTOK);
;                     attn_unit<1>(lds, gb, PROJ + r0 * NPAD + PC_MQ + hm * 128, NPAD, (const bf16_t*)(p.ws + WS_CMK) + (size_t)(sq * MEMT) * 512 + hm * 128, (const bf16_t*)(p.ws + WS_CMV) + (size_t)(sq * MEMT) * 512 + hm * 128, 512,
;                                  4, 0, DTOK, 0.f, PROJ + r0 * NPAD + PC_GM + hm * 128, NPAD, MIX + r0 * 2048 + 1536 + hm * 128, 2048); } })
.LBB0_883:
	s_mov_b32 s5, 0x8000
	v_mov_b32_e32 v2, 0
.Lmem_poll:
	global_load_dword v1, v2, s[90:91] offset:2048 sc1
	s_waitcnt vmcnt(0)
	v_readfirstlane_b32 s4, v1
	s_cmpk_gt_u32 s4, 0xff
	s_cbranch_scc1 .Lmem_poll_done
	s_add_i32 s5, s5, -1
	s_cmp_eq_u32 s5, 0
	s_cbranch_scc1 .Lmem_poll_done
	s_sleep 8
	s_branch .Lmem_poll
.Lmem_poll_done:
	buffer_inv sc1
	s_waitcnt vmcnt(0)
	s_add_u32 s26, s90, 0xd700000
	s_addc_u32 s27, s91, 0
	s_add_u32 s29, s90, 0xda00000
	s_addc_u32 s30, s91, 0
	s_add_u32 s31, s90, 0xd300000
	s_addc_u32 s34, s91, 0
	s_add_u32 s35, s90, 0xd500000
	s_addc_u32 s44, s91, 0
	s_add_i32 s46, 0, 0x27e50
	s_mov_b32 s7, 0
	s_waitcnt vmcnt(4)
	v_mov_b32_e32 v147, 0
	v_mov_b32_e32 v1, s46
	s_movk_i32 s47, 0x11f
	s_movk_i32 s50, 0x3600
	s_movk_i32 s51, 0x70
	s_mov_b32 s53, 0xfffff0
	s_movk_i32 s54, 0xc0
	s_movk_i32 s55, 0x60
	s_movk_i32 s62, 0x80
	s_movk_i32 s63, 0xa0
	s_movk_i32 s64, 0xe0
	s_movk_i32 s65, 0x118
	s_mov_b64 s[8:9], 0x4000
	s_mov_b64 s[10:11], 0x8000
	s_mov_b64 s[12:13], 0xc000
	s_mov_b64 s[14:15], 0xc00
	s_mov_b32 s66, 0
	s_branch .LBB0_886

; #define LAS __attribute__((address_space(3)))
; __device__ __forceinline__ unsigned cvtpk(float lo, float hi) { unsigned r; asm volatile("v_cvt_pk_bf16_f32 %0, %1, %2" : "=v"(r) : "v"(lo), "v"(hi)); return r; }
; #define DLOAD(dst, rs, kb) do { _Pragma("unroll") for (int i = 0; i < 8; ++i) { const int so_ = ((kb) * 32 + 4 * i) * 4096; \
;         dst[2 * i] = __builtin_bit_cast(f32x4, __builtin_amdgcn_raw_buffer_load_b128(rs, voff, so_, 2)); dst[2 * i + 1] = __builtin_bit_cast(f32x4, __builtin_amdgcn_raw_buffer_load_b128(rs, voff + 16, so_, 2)); } } while (0)
; __device__ __forceinline__ void decode_page(const int* ptab, const float* ck, const float* cv, const float* sbbias, unsigned char* ws, LAS unsigned char* wlds, int seq, int page, int head, int lane) {
;     ...
; #pragma unroll
;         for (int i = 0; i < 8; ++i) { u32x4 w; w.x = cvtpk(sk[2 * i].x, sk[2 * i].y); w.y = cvtpk(sk[2 * i].z, sk[2 * i].w); w.z = cvtpk(sk[2 * i + 1].x, sk[2 * i + 1].y); w.w = cvtpk(sk[2 * i + 1].z, sk[2 * i + 1].w);
;             *(LAS u32x4*)(K_lds + KSWZ(srow + 4 * i, scol * 2)) = w; }
;         if (kb > 0) DLOAD(sk, rK, kb - 1);
;         f32x4 st[2];
;         st[0] = f32x4{bias2, bias2, bias2, bias2}; st[1] = st[0];
; #pragma unroll
;         for (int ks = 0; ks < 4; ++ks) { const int cb = (32 * ks + 8 * kg) * 2;
;             const bf16x8 qf = *(const LAS bf16x8*)(Q_lds + KSWZ(j16 & 7, cb));
;             const bf16x8 k0 = *(const LAS bf16x8*)(K_lds + KSWZ(j16, cb)), k1 = *(const LAS bf16x8*)(K_lds + KSWZ(16 + j16, cb));
;             st[0] = __builtin_amdgcn_mfma_f32_16x16x32_bf16(k0, qf, st[0], 0, 0, 0);
;             st[1] = __builtin_amdgcn_mfma_f32_16x16x32_bf16(k1, qf, st[1], 0, 0, 0); }
.LBB0_989:
	s_waitcnt vmcnt(31)
	v_cvt_pk_bf16_f32 v166, v42, v43
	v_cvt_pk_bf16_f32 v167, v44, v45
	s_waitcnt vmcnt(29)
	v_cvt_pk_bf16_f32 v168, v58, v59
	v_cvt_pk_bf16_f32 v169, v60, v61
	v_add_u32_e32 v223, v182, v196
	ds_write_b128 v223, v[166:169]
	v_cvt_pk_bf16_f32 v166, v6, v7
	v_cvt_pk_bf16_f32 v167, v8, v9
	s_waitcnt vmcnt(28)
	v_cvt_pk_bf16_f32 v168, v14, v15
	v_cvt_pk_bf16_f32 v169, v16, v17
	ds_write_b128 v202, v[166:169]
	s_waitcnt vmcnt(27)
	v_cvt_pk_bf16_f32 v166, v10, v11
	v_cvt_pk_bf16_f32 v167, v12, v13
	s_waitcnt vmcnt(25)
	v_cvt_pk_bf16_f32 v168, v18, v19
	v_cvt_pk_bf16_f32 v169, v20, v21
	ds_write_b128 v203, v[166:169]
	v_cvt_pk_bf16_f32 v166, v22, v23
	v_cvt_pk_bf16_f32 v167, v24, v25
	s_waitcnt vmcnt(24)
	v_cvt_pk_bf16_f32 v168, v30, v31
	v_cvt_pk_bf16_f32 v169, v32, v33
	ds_write_b128 v204, v[166:169]
	s_waitcnt vmcnt(23)
	v_cvt_pk_bf16_f32 v166, v26, v27
	v_cvt_pk_bf16_f32 v167, v28, v29
	s_waitcnt vmcnt(21)
	v_cvt_pk_bf16_f32 v168, v38, v39
	v_cvt_pk_bf16_f32 v169, v40, v41
	s_cmp_lg_u32 s44, 0xfffe0000
	ds_write_b128 v205, v[166:169]
	v_cvt_pk_bf16_f32 v166, v54, v55
	v_cvt_pk_bf16_f32 v167, v56, v57
	s_waitcnt vmcnt(20)
	v_cvt_pk_bf16_f32 v168, v70, v71
	v_cvt_pk_bf16_f32 v169, v72, v73
	s_cselect_b64 s[22:23], -1, 0
	ds_write_b128 v206, v[166:169]
	s_waitcnt vmcnt(19)
	v_cvt_pk_bf16_f32 v166, v66, v67
	v_cvt_pk_bf16_f32 v167, v68, v69
	s_waitcnt vmcnt(17)
	v_cvt_pk_bf16_f32 v168, v82, v83
	v_cvt_pk_bf16_f32 v169, v84, v85
	s_and_b64 vcc, exec, s[22:23]
	ds_write_b128 v207, v[166:169]
	v_cvt_pk_bf16_f32 v166, v90, v91
	v_cvt_pk_bf16_f32 v167, v92, v93
	s_waitcnt vmcnt(16)
	v_cvt_pk_bf16_f32 v168, v102, v103
	v_cvt_pk_bf16_f32 v169, v104, v105
	ds_write_b128 v208, v[166:169]
	s_cbranch_vccz .Ldec_lastblk
	s_add_i32 s25, s44, 0x4000
	buffer_load_dwordx4 v[42:45], v175, s[16:19], s44 offen nt
	buffer_load_dwordx4 v[6:9], v175, s[16:19], s25 offen nt
	buffer_load_dwordx4 v[58:61], v177, s[16:19], s44 offen nt
	buffer_load_dwordx4 v[14:17], v177, s[16:19], s25 offen nt
	s_add_i32 s78, s44, 0x8000
	s_add_i32 s25, s44, 0xc000
	buffer_load_dwordx4 v[10:13], v175, s[16:19], s78 offen nt
	buffer_load_dwordx4 v[22:25], v175, s[16:19], s25 offen nt
	buffer_load_dwordx4 v[18:21], v177, s[16:19], s78 offen nt
	buffer_load_dwordx4 v[30:33], v177, s[16:19], s25 offen nt
	s_add_i32 s78, s44, 0x10000
	s_add_i32 s25, s44, 0x14000
	buffer_load_dwordx4 v[26:29], v175, s[16:19], s78 offen nt
	buffer_load_dwordx4 v[54:57], v175, s[16:19], s25 offen nt
	buffer_load_dwordx4 v[38:41], v177, s[16:19], s78 offen nt
	buffer_load_dwordx4 v[70:73], v177, s[16:19], s25 offen nt
	s_add_i32 s78, s44, 0x18000
	s_add_i32 s25, s44, 0x1c000
	buffer_load_dwordx4 v[66:69], v175, s[16:19], s78 offen nt
	buffer_load_dwordx4 v[90:93], v175, s[16:19], s25 offen nt
	buffer_load_dwordx4 v[82:85], v177, s[16:19], s78 offen nt
	buffer_load_dwordx4 v[102:105], v177, s[16:19], s25 offen nt
.LBB0_991:
	ds_read_b128 v[166:169], v209 offset:4096
	v_add_u32_e32 v223, v186, v193
	v_add_u32_e32 v228, v187, v193
	ds_read_b128 v[224:227], v223 offset:16896
	ds_read_b128 v[228:231], v228
	v_add_u32_e32 v223, v186, v197
	v_add_u32_e32 v236, v187, v197
	ds_read_b128 v[232:235], v223 offset:16896
	ds_read_b128 v[236:239], v236
	v_add_u32_e32 v223, v187, v198
	s_waitcnt lgkmcnt(3)
	v_mfma_f32_16x16x32_bf16 v[166:169], v[166:169], v[224:227], v[62:65]
	s_andn2_b64 vcc, exec, s[22:23]
	s_waitcnt lgkmcnt(2)
	v_mfma_f32_16x16x32_bf16 v[224:227], v[228:231], v[224:227], v[62:65]
	ds_read_b128 v[228:231], v210 offset:4096
	s_waitcnt lgkmcnt(1)
	v_mfma_f32_16x16x32_bf16 v[224:227], v[236:239], v[232:235], v[224:227]
	ds_read_b128 v[236:239], v223
	v_add_u32_e32 v223, v186, v198
	s_waitcnt lgkmcnt(1)
	v_mfma_f32_16x16x32_bf16 v[166:169], v[228:231], v[232:235], v[166:169]
	ds_read_b128 v[228:231], v223 offset:16896
	ds_read_b128 v[232:235], v211 offset:4096
	v_add_u32_e32 v223, v186, v199
	s_waitcnt lgkmcnt(1)
	v_mfma_f32_16x16x32_bf16 v[224:227], v[236:239], v[228:231], v[224:227]
	ds_read_b128 v[236:239], v223 offset:16896
	v_add_u32_e32 v223, v187, v199
	s_waitcnt lgkmcnt(1)
	v_mfma_f32_16x16x32_bf16 v[166:169], v[232:235], v[228:231], v[166:169]
	ds_read_b128 v[228:231], v223
	ds_read_b128 v[232:235], v212 offset:4096
	s_waitcnt lgkmcnt(1)
	v_mfma_f32_16x16x32_bf16 v[224:227], v[228:231], v[236:239], v[224:227]
	s_waitcnt lgkmcnt(0)
; #define LAS __attribute__((address_space(3)))
; __device__ __forceinline__ void sb_transform16(f32x4 (&st)[2], float& R, int lane, int kg) {
;     float T[2];
; #pragma unroll
;     for (int rb = 0; rb < 2; ++rb) {
;         float be[4], f[4];
; #pragma unroll
;         for (int i = 0; i < 4; ++i) { const float z = fmaxf(st[rb][i], -100.f); const float e = fast_exp2(-z), rc = fast_rcp(1.f + e); be[i] = rc; f[i] = e * rc; }
;         const float e2 = f[3], e1 = f[2] * f[3], e0 = f[1] * e1;
;         T[rb] = f[0] * e0;
;         st[rb][0] = be[0] * e0; st[rb][1] = be[1] * e1; st[rb][2] = be[2] * e2; st[rb][3] = be[3];
;     }
;     float Tg[8];
; #pragma unroll
;     for (int k2 = 0; k2 < 4; ++k2) { const int src = ((lane & 15) + 16 * k2) * 4;
;         Tg[k2] = __builtin_bit_cast(float, __builtin_amdgcn_ds_bpermute(src, __builtin_bit_cast(int, T[0])));
;         Tg[4 + k2] = __builtin_bit_cast(float, __builtin_amdgcn_ds_bpermute(src, __builtin_bit_cast(int, T[1]))); }
;     float S[8]; S[7] = R;
; #pragma unroll
;     for (int G = 6; G >= 0; --G) S[G] = S[G + 1] * Tg[G + 1];
; __device__ __forceinline__ void decode_page(const int* ptab, const float* ck, const float* cv, const float* sbbias, unsigned char* ws, LAS unsigned char* wlds, int seq, int page, int head, int lane) {
;     ...
;         for (int ks = 0; ks < 4; ++ks) { const int cb = (32 * ks + 8 * kg) * 2;
;             const bf16x8 qf = *(const LAS bf16x8*)(Q_lds + KSWZ(j16 & 7, cb));
;             const bf16x8 k0 = *(const LAS bf16x8*)(K_lds + KSWZ(j16, cb)), k1 = *(const LAS bf16x8*)(K_lds + KSWZ(16 + j16, cb));
;             st[0] = __builtin_amdgcn_mfma_f32_16x16x32_bf16(k0, qf, st[0], 0, 0, 0);
;             st[1] = __builtin_amdgcn_mfma_f32_16x16x32_bf16(k1, qf, st[1], 0, 0, 0); }
;         sb_transform16(st, R, lane, kg);
;         u32x4 af; af.x = cvtpk(st[0][0], st[0][1]); af.y = cvtpk(st[0][2], st[0][3]); af.z = cvtpk(st[1][0], st[1][1]); af.w = cvtpk(st[1][2], st[1][3]);
;         const bf16x8 pfrag = __builtin_bit_cast(bf16x8, af);
; #pragma unroll
;         for (int i = 0; i < 8; ++i) { u32x4 w; w.x = cvtpk(sv[2 * i].x, sv[2 * i].y); w.y = cvtpk(sv[2 * i].z, sv[2 * i].w); w.z = cvtpk(sv[2 * i + 1].x, sv[2 * i + 1].y); w.w = cvtpk(sv[2 * i + 1].z, sv[2 * i + 1].w);
;             *(LAS u32x4*)(V_lds + (srow + 4 * i) * VLD + scol * 2) = w; }
;         if (kb > 0) DLOAD(sv, rV, kb - 1);
	v_mfma_f32_16x16x32_bf16 v[166:169], v[232:235], v[236:239], v[166:169]
	s_nop 5
	v_max_f32_e64 v223, -v225, -v225
	v_min_f32_e32 v223, 0x42c80000, v223
	v_max_f32_e64 v226, -v226, -v226
	v_exp_f32_e32 v223, v223
	v_min_f32_e32 v226, 0x42c80000, v226
	v_max_f32_e64 v227, -v227, -v227
	v_exp_f32_e32 v226, v226
	v_min_f32_e32 v227, 0x42c80000, v227
	v_exp_f32_e32 v227, v227
	v_max_f32_e64 v224, -v224, -v224
	v_min_f32_e32 v224, 0x42c80000, v224
	v_add_f32_e32 v225, 1.0, v223
	v_exp_f32_e32 v224, v224
	v_rcp_f32_e32 v236, v225
	v_add_f32_e32 v225, 1.0, v226
	v_rcp_f32_e32 v228, v225
	v_add_f32_e32 v225, 1.0, v227
	v_rcp_f32_e32 v229, v225
	v_max_f32_e64 v168, -v168, -v168
	v_max_f32_e64 v169, -v169, -v169
	v_min_f32_e32 v168, 0x42c80000, v168
	v_min_f32_e32 v169, 0x42c80000, v169
	v_add_f32_e32 v225, 1.0, v224
	v_max_f32_e64 v167, -v167, -v167
	v_exp_f32_e32 v168, v168
	v_exp_f32_e32 v169, v169
	v_rcp_f32_e32 v230, v225
	v_min_f32_e32 v167, 0x42c80000, v167
	v_max_f32_e64 v166, -v166, -v166
	v_pk_mul_f32 v[226:227], v[226:227], v[228:229]
	v_exp_f32_e32 v167, v167
	v_min_f32_e32 v166, 0x42c80000, v166
	v_pk_mul_f32 v[232:233], v[226:227], v[226:227] op_sel:[0,1] op_sel_hi:[1,0]
	v_exp_f32_e32 v166, v166
	v_mul_f32_e32 v225, v223, v236
	v_mov_b32_e32 v231, v232
	v_mul_f32_e32 v228, v228, v227
	v_add_f32_e32 v226, 1.0, v168
	v_add_f32_e32 v227, 1.0, v169
	v_pk_mul_f32 v[224:225], v[224:225], v[230:231]
	v_rcp_f32_e32 v226, v226
	v_rcp_f32_e32 v227, v227
	v_pk_mul_f32 v[234:235], v[224:225], v[224:225] op_sel:[0,1] op_sel_hi:[1,0]
	v_mov_b32_e32 v231, v236
	v_pk_mov_b32 v[224:225], v[224:225], v[232:233] op_sel:[1,0]
	v_add_f32_e32 v223, 1.0, v167
	v_pk_mul_f32 v[224:225], v[230:231], v[224:225]
	v_rcp_f32_e32 v223, v223
	v_add_f32_e32 v230, 1.0, v166
	v_rcp_f32_e32 v230, v230
	v_pk_mul_f32 v[168:169], v[168:169], v[226:227]
	v_mul_f32_e32 v167, v167, v223
	v_pk_mul_f32 v[232:233], v[168:169], v[168:169] op_sel:[0,1] op_sel_hi:[1,0]
	v_mul_f32_e32 v226, v226, v169
	v_mov_b32_e32 v231, v232
	v_pk_mul_f32 v[166:167], v[166:167], v[230:231]
	v_mov_b32_e32 v231, v223
	v_pk_mul_f32 v[236:237], v[166:167], v[166:167] op_sel:[0,1] op_sel_hi:[1,0]
	v_pk_mov_b32 v[166:167], v[166:167], v[232:233] op_sel:[1,0]
	ds_bpermute_b32 v223, v195, v236
	v_pk_mul_f32 v[166:167], v[230:231], v[166:167]
	ds_bpermute_b32 v230, v194, v236
	ds_bpermute_b32 v231, v189, v236
	ds_bpermute_b32 v168, v188, v236
	ds_bpermute_b32 v233, v195, v234
	ds_bpermute_b32 v232, v194, v234
	s_waitcnt lgkmcnt(5)
	v_mul_f32_e32 v235, v222, v223
	ds_bpermute_b32 v169, v189, v234
	s_waitcnt lgkmcnt(5)
	v_mul_f32_e32 v230, v235, v230
	s_waitcnt lgkmcnt(4)
	v_mul_f32_e32 v231, v230, v231
	s_waitcnt lgkmcnt(3)
	v_mul_f32_e32 v168, v231, v168
	s_waitcnt lgkmcnt(2)
	v_mul_f32_e32 v233, v168, v233
	s_waitcnt lgkmcnt(1)
	v_mul_f32_e32 v232, v233, v232
	s_waitcnt lgkmcnt(0)
	v_mul_f32_e32 v223, v232, v169
	v_cndmask_b32_e64 v168, v168, v233, s[8:9]
	v_cndmask_b32_e64 v169, v222, v235, s[8:9]
	v_cndmask_b32_e64 v168, v168, v232, s[6:7]
	v_cndmask_b32_e64 v169, v169, v230, s[6:7]
	v_cndmask_b32_e64 v168, v168, v223, s[4:5]
	v_cndmask_b32_e64 v222, v169, v231, s[4:5]
	v_pk_mul_f32 v[228:229], v[228:229], v[168:169] op_sel_hi:[1,0]
	v_pk_mul_f32 v[168:169], v[224:225], v[168:169] op_sel_hi:[1,0]
	v_pk_mul_f32 v[224:225], v[226:227], v[222:223] op_sel_hi:[1,0]
	v_pk_mul_f32 v[226:227], v[166:167], v[222:223] op_sel_hi:[1,0]
	v_cvt_pk_bf16_f32 v166, v168, v169
	v_cvt_pk_bf16_f32 v167, v228, v229
	ds_bpermute_b32 v222, v188, v234
	v_cvt_pk_bf16_f32 v168, v226, v227
	v_cvt_pk_bf16_f32 v169, v224, v225
	s_waitcnt vmcnt(31)
	v_cvt_pk_bf16_f32 v224, v106, v107
	v_cvt_pk_bf16_f32 v225, v108, v109
	s_waitcnt vmcnt(29)
	v_cvt_pk_bf16_f32 v226, v118, v119
	v_cvt_pk_bf16_f32 v227, v120, v121
	ds_write_b128 v213, v[224:227] offset:8192
	v_cvt_pk_bf16_f32 v224, v34, v35
	v_cvt_pk_bf16_f32 v225, v36, v37
	s_waitcnt vmcnt(28)
	v_cvt_pk_bf16_f32 v226, v50, v51
	v_cvt_pk_bf16_f32 v227, v52, v53
	ds_write_b128 v213, v[224:227] offset:9280
	s_waitcnt vmcnt(27)
	v_cvt_pk_bf16_f32 v224, v46, v47
	v_cvt_pk_bf16_f32 v225, v48, v49
	s_waitcnt vmcnt(25)
	v_cvt_pk_bf16_f32 v226, v74, v75
	v_cvt_pk_bf16_f32 v227, v76, v77
	ds_write_b128 v213, v[224:227] offset:10368
	v_cvt_pk_bf16_f32 v224, v86, v87
	v_cvt_pk_bf16_f32 v225, v88, v89
	s_waitcnt vmcnt(24)
	v_cvt_pk_bf16_f32 v226, v98, v99
	v_cvt_pk_bf16_f32 v227, v100, v101
	ds_write_b128 v213, v[224:227] offset:11456
	s_waitcnt vmcnt(23)
	v_cvt_pk_bf16_f32 v224, v94, v95
	v_cvt_pk_bf16_f32 v225, v96, v97
	s_waitcnt vmcnt(21)
	v_cvt_pk_bf16_f32 v226, v114, v115
	v_cvt_pk_bf16_f32 v227, v116, v117
	ds_write_b128 v213, v[224:227] offset:12544
	v_cvt_pk_bf16_f32 v224, v122, v123
	v_cvt_pk_bf16_f32 v225, v124, v125
	s_waitcnt vmcnt(20)
	v_cvt_pk_bf16_f32 v226, v134, v135
	v_cvt_pk_bf16_f32 v227, v136, v137
	ds_write_b128 v213, v[224:227] offset:13632
	s_waitcnt vmcnt(19)
	v_cvt_pk_bf16_f32 v224, v130, v131
	v_cvt_pk_bf16_f32 v225, v132, v133
	s_waitcnt vmcnt(17)
	v_cvt_pk_bf16_f32 v226, v138, v139
	v_cvt_pk_bf16_f32 v227, v140, v141
	ds_write_b128 v213, v[224:227] offset:14720
	v_cvt_pk_bf16_f32 v224, v146, v147
	v_cvt_pk_bf16_f32 v225, v148, v149
	s_waitcnt vmcnt(16)
	v_cvt_pk_bf16_f32 v226, v150, v151
	v_cvt_pk_bf16_f32 v227, v152, v153
	ds_write_b128 v213, v[224:227] offset:15808
	s_cbranch_vccnz .LBB0_988
	s_mov_b32 s22, s18
	s_mov_b32 s23, s19
	s_add_i32 s25, s44, 0x4000
	buffer_load_dwordx4 v[106:109], v175, s[20:23], s44 offen nt
	buffer_load_dwordx4 v[34:37], v175, s[20:23], s25 offen nt
	buffer_load_dwordx4 v[118:121], v177, s[20:23], s44 offen nt
	buffer_load_dwordx4 v[50:53], v177, s[20:23], s25 offen nt
	s_add_i32 s78, s44, 0x8000
	s_add_i32 s25, s44, 0xc000
	buffer_load_dwordx4 v[46:49], v175, s[20:23], s78 offen nt
	buffer_load_dwordx4 v[86:89], v175, s[20:23], s25 offen nt
	buffer_load_dwordx4 v[74:77], v177, s[20:23], s78 offen nt
	buffer_load_dwordx4 v[98:101], v177, s[20:23], s25 offen nt
	s_add_i32 s78, s44, 0x10000
	s_add_i32 s25, s44, 0x14000
	buffer_load_dwordx4 v[94:97], v175, s[20:23], s78 offen nt
	buffer_load_dwordx4 v[122:125], v175, s[20:23], s25 offen nt
	buffer_load_dwordx4 v[114:117], v177, s[20:23], s78 offen nt
	buffer_load_dwordx4 v[134:137], v177, s[20:23], s25 offen nt
	s_add_i32 s78, s44, 0x18000
	s_add_i32 s25, s44, 0x1c000
	buffer_load_dwordx4 v[130:133], v175, s[20:23], s78 offen nt
	buffer_load_dwordx4 v[146:149], v175, s[20:23], s25 offen nt
	buffer_load_dwordx4 v[138:141], v177, s[20:23], s78 offen nt
	buffer_load_dwordx4 v[150:153], v177, s[20:23], s25 offen nt
	s_branch .LBB0_988
.Ldec_lastblk:
	s_waitcnt vmcnt(0)
	s_branch .LBB0_991

; #define LAS __attribute__((address_space(3)))
; __global__ void __launch_bounds__(512, 2) hymba_fwd(Params p) {
;     extern __shared__ __attribute__((aligned(16))) unsigned char lds_raw[];
;     LAS unsigned char* lds = (LAS unsigned char*)lds_raw;
	.amdhsa_kernel _Z9hymba_fwd6Params
		.amdhsa_group_segment_fixed_size 0
		.amdhsa_private_segment_fixed_size 0
		.amdhsa_kernarg_size 488
		.amdhsa_user_sgpr_count 2
		.amdhsa_user_sgpr_dispatch_ptr 0
		.amdhsa_user_sgpr_queue_ptr 0
		.amdhsa_user_sgpr_kernarg_segment_ptr 1
		.amdhsa_user_sgpr_dispatch_id 0
		.amdhsa_user_sgpr_kernarg_preload_length 0
		.amdhsa_user_sgpr_kernarg_preload_offset 0
		.amdhsa_user_sgpr_private_segment_size 0
		.amdhsa_uses_dynamic_stack 0
		.amdhsa_enable_private_segment 0
		.amdhsa_system_sgpr_workgroup_id_x 1
		.amdhsa_system_sgpr_workgroup_id_y 0
		.amdhsa_system_sgpr_workgroup_id_z 0
		.amdhsa_system_sgpr_workgroup_info 0
		.amdhsa_system_vgpr_workitem_id 0
		.amdhsa_next_free_vgpr 255
		.amdhsa_next_free_sgpr 102
		.amdhsa_accum_offset 256
		.amdhsa_reserve_vcc 1
		.amdhsa_float_round_mode_32 0
		.amdhsa_float_round_mode_16_64 0
		.amdhsa_float_denorm_mode_32 3
		.amdhsa_float_denorm_mode_16_64 3
		.amdhsa_dx10_clamp 1
		.amdhsa_ieee_mode 1
		.amdhsa_fp16_overflow 0
		.amdhsa_tg_split 0
		.amdhsa_exception_fp_ieee_invalid_op 0
		.amdhsa_exception_fp_denorm_src 0
		.amdhsa_exception_fp_ieee_div_zero 0
		.amdhsa_exception_fp_ieee_overflow 0
		.amdhsa_exception_fp_ieee_underflow 0
		.amdhsa_exception_fp_ieee_inexact 0
		.amdhsa_exception_int_div_zero 0
	.end_amdhsa_kernel

; #define LAS __attribute__((address_space(3)))
; __global__ void __launch_bounds__(512, 2) hymba_fwd(Params p) {
;     extern __shared__ __attribute__((aligned(16))) unsigned char lds_raw[];
;     LAS unsigned char* lds = (LAS unsigned char*)lds_raw;
amdhsa.kernels:
  - .agpr_count:     0
    .args:
      - .offset:         0
        .size:           232
        .value_kind:     by_value
      - .offset:         232
        .size:           4
        .value_kind:     hidden_block_count_x
      - .offset:         236
        .size:           4
        .value_kind:     hidden_block_count_y
      - .offset:         240
        .size:           4
        .value_kind:     hidden_block_count_z
      - .offset:         244
        .size:           2
        .value_kind:     hidden_group_size_x
      - .offset:         246
        .size:           2
        .value_kind:     hidden_group_size_y
      - .offset:         248
        .size:           2
        .value_kind:     hidden_group_size_z
      - .offset:         250
        .size:           2
        .value_kind:     hidden_remainder_x
      - .offset:         252
        .size:           2
        .value_kind:     hidden_remainder_y
      - .offset:         254
        .size:           2
        .value_kind:     hidden_remainder_z
      - .offset:         272
        .size:           8
        .value_kind:     hidden_global_offset_x
      - .offset:         280
        .size:           8
        .value_kind:     hidden_global_offset_y
      - .offset:         288
        .size:           8
        .value_kind:     hidden_global_offset_z
      - .offset:         296
        .size:           2
        .value_kind:     hidden_grid_dims
      - .offset:         352
        .size:           4
        .value_kind:     hidden_dynamic_lds_size
    .group_segment_fixed_size: 0
    .kernarg_segment_align: 8
    .kernarg_segment_size: 488
    .language:       OpenCL C
    .language_version:
      - 2
      - 0
    .max_flat_workgroup_size: 512
    .name:           _Z9hymba_fwd6Params
    .private_segment_fixed_size: 0
    .sgpr_count:     108
    .sgpr_spill_count: 48
    .symbol:         _Z9hymba_fwd6Params.kd
    .uniform_work_group_size: 1
    .uses_dynamic_stack: false
    .vgpr_count:     255
    .vgpr_spill_count: 0
    .wavefront_size: 64
